# v140 + 64-byte alignment of the GEMM K-loop head and the attention key-loop head
# speedup vs baseline: 1.0020x; 1.0020x over previous
.Lat_prio_10:
	s_lshl_b32 s4, s57, 5
	s_add_u32 s4, s4, s70
	s_add_u32 s4, s4, s83
	s_cmpk_ge_u32 s4, 0x180
	s_cselect_b32 s5, 0x180, 0
	s_sub_u32 s69, s4, s5
	s_mul_i32 s4, s69, 0x90
	v_add_u32_e32 v216, s4, v8
	v_add_u32_e32 v217, s4, v9
	ds_read_b128 v[148:151], v216 offset:0
	ds_read_b128 v[152:155], v216 offset:32
	ds_read_b128 v[156:159], v216 offset:64
	ds_read_b128 v[160:163], v216 offset:96
	ds_read_b64_tr_b16 v[176:177], v217 offset:0
	ds_read_b64_tr_b16 v[178:179], v217 offset:1152
	ds_read_b64_tr_b16 v[180:181], v217 offset:2304
	ds_read_b64_tr_b16 v[182:183], v217 offset:3456
	ds_read_b64_tr_b16 v[184:185], v217 offset:64
	ds_read_b64_tr_b16 v[186:187], v217 offset:1216
	ds_read_b64_tr_b16 v[188:189], v217 offset:2368
	ds_read_b64_tr_b16 v[190:191], v217 offset:3520
	.p2align	6

.LBB0_462:
	s_add_u32 s4, s6, 0x80
	s_addc_u32 s5, s7, 0
	s_add_u32 s3, s8, 0x100
	v_mov_b32_e32 v2, 0
	s_addc_u32 s8, s9, 0
	s_mov_b32 s6, 0
	v_mov_b32_e32 v3, v2
	v_mov_b32_e32 v4, v2
	v_mov_b32_e32 v5, v2
	v_mov_b32_e32 v6, v2
	v_mov_b32_e32 v7, v2
	v_mov_b32_e32 v8, v2
	v_mov_b32_e32 v9, v2
	v_mov_b32_e32 v18, v2
	v_mov_b32_e32 v19, v2
	v_mov_b32_e32 v20, v2
	v_mov_b32_e32 v21, v2
	v_mov_b32_e32 v22, v2
	v_mov_b32_e32 v23, v2
	v_mov_b32_e32 v24, v2
	v_mov_b32_e32 v25, v2
	v_mov_b32_e32 v34, v2
	v_mov_b32_e32 v35, v2
	v_mov_b32_e32 v36, v2
	v_mov_b32_e32 v37, v2
	v_mov_b32_e32 v38, v2
	v_mov_b32_e32 v39, v2
	v_mov_b32_e32 v40, v2
	v_mov_b32_e32 v41, v2
	v_mov_b32_e32 v50, v2
	v_mov_b32_e32 v51, v2
	v_mov_b32_e32 v52, v2
	v_mov_b32_e32 v53, v2
	v_mov_b32_e32 v54, v2
	v_mov_b32_e32 v55, v2
	v_mov_b32_e32 v56, v2
	v_mov_b32_e32 v57, v2
	v_mov_b32_e32 v10, v2
	v_mov_b32_e32 v11, v2
	v_mov_b32_e32 v12, v2
	v_mov_b32_e32 v13, v2
	v_mov_b32_e32 v14, v2
	v_mov_b32_e32 v15, v2
	v_mov_b32_e32 v16, v2
	v_mov_b32_e32 v17, v2
	v_mov_b32_e32 v26, v2
	v_mov_b32_e32 v27, v2
	v_mov_b32_e32 v28, v2
	v_mov_b32_e32 v29, v2
	v_mov_b32_e32 v30, v2
	v_mov_b32_e32 v31, v2
	v_mov_b32_e32 v32, v2
	v_mov_b32_e32 v33, v2
	v_mov_b32_e32 v42, v2
	v_mov_b32_e32 v43, v2
	v_mov_b32_e32 v44, v2
	v_mov_b32_e32 v45, v2
	v_mov_b32_e32 v46, v2
	v_mov_b32_e32 v47, v2
	v_mov_b32_e32 v48, v2
	v_mov_b32_e32 v49, v2
	v_mov_b32_e32 v58, v2
	v_mov_b32_e32 v59, v2
	v_mov_b32_e32 v60, v2
	v_mov_b32_e32 v61, v2
	v_mov_b32_e32 v62, v2
	v_mov_b32_e32 v63, v2
	s_waitcnt vmcnt(0)
	v_mov_b32_e32 v64, v2
	v_mov_b32_e32 v65, v2
	v_mov_b32_e32 v66, v2
	v_mov_b32_e32 v67, v2
	v_mov_b32_e32 v68, v2
	v_mov_b32_e32 v69, v2
	v_mov_b32_e32 v70, v2
	v_mov_b32_e32 v71, v2
	v_mov_b32_e32 v72, v2
	v_mov_b32_e32 v73, v2
	v_mov_b32_e32 v82, v2
	v_mov_b32_e32 v83, v2
	v_mov_b32_e32 v84, v2
	v_mov_b32_e32 v85, v2
	v_mov_b32_e32 v86, v2
	v_mov_b32_e32 v87, v2
	v_mov_b32_e32 v88, v2
	v_mov_b32_e32 v89, v2
	v_mov_b32_e32 v98, v2
	v_mov_b32_e32 v99, v2
	v_mov_b32_e32 v100, v2
	v_mov_b32_e32 v101, v2
	v_mov_b32_e32 v102, v2
	v_mov_b32_e32 v103, v2
	v_mov_b32_e32 v104, v2
	v_mov_b32_e32 v105, v2
	v_mov_b32_e32 v120, v2
	v_mov_b32_e32 v121, v2
	v_mov_b32_e32 v122, v2
	v_mov_b32_e32 v123, v2
	v_mov_b32_e32 v124, v2
	v_mov_b32_e32 v125, v2
	v_mov_b32_e32 v126, v2
	v_mov_b32_e32 v127, v2
	v_mov_b32_e32 v74, v2
	v_mov_b32_e32 v75, v2
	v_mov_b32_e32 v76, v2
	v_mov_b32_e32 v77, v2
	v_mov_b32_e32 v78, v2
	v_mov_b32_e32 v79, v2
	v_mov_b32_e32 v80, v2
	v_mov_b32_e32 v81, v2
	v_mov_b32_e32 v90, v2
	v_mov_b32_e32 v91, v2
	v_mov_b32_e32 v92, v2
	v_mov_b32_e32 v93, v2
	v_mov_b32_e32 v94, v2
	v_mov_b32_e32 v95, v2
	v_mov_b32_e32 v96, v2
	v_mov_b32_e32 v97, v2
	v_mov_b32_e32 v106, v2
	v_mov_b32_e32 v107, v2
	v_mov_b32_e32 v108, v2
	v_mov_b32_e32 v109, v2
	v_mov_b32_e32 v116, v2
	v_mov_b32_e32 v117, v2
	v_mov_b32_e32 v118, v2
	v_mov_b32_e32 v119, v2
	v_mov_b32_e32 v128, v2
	v_mov_b32_e32 v129, v2
	v_mov_b32_e32 v130, v2
	v_mov_b32_e32 v131, v2
	v_mov_b32_e32 v132, v2
	v_mov_b32_e32 v133, v2
	v_mov_b32_e32 v134, v2
	v_mov_b32_e32 v135, v2
	.p2align	6
